# the eight GEMM main-loop heads aligned to 64 bytes (s_nop fill)
# speedup vs baseline: 1.0005x; 1.0005x over previous
.LBB0_315:
	s_ashr_i32 s65, s64, 31
	s_lshl_b64 s[0:1], s[64:65], 20
	s_add_u32 s70, s20, s0
	s_addc_u32 s71, s21, s1
	s_and_b64 s[0:1], s[8:9], exec
	s_cselect_b32 s0, s71, s75
	s_cselect_b32 s1, s70, s74
	s_add_u32 s8, s76, 0x80080
	s_addc_u32 s9, s77, 0
	s_add_u32 s12, s74, 0x100
	v_mov_b32_e32 v0, 0
	s_addc_u32 s24, s75, 0
	s_mov_b32 s25, -2
	v_mov_b32_e32 v1, v0
	v_mov_b32_e32 v2, v0
	v_mov_b32_e32 v3, v0
	v_mov_b32_e32 v4, v0
	v_mov_b32_e32 v5, v0
	v_mov_b32_e32 v6, v0
	v_mov_b32_e32 v7, v0
	v_mov_b32_e32 v8, v0
	v_mov_b32_e32 v9, v0
	v_mov_b32_e32 v10, v0
	v_mov_b32_e32 v11, v0
	v_mov_b32_e32 v12, v0
	v_mov_b32_e32 v13, v0
	v_mov_b32_e32 v14, v0
	v_mov_b32_e32 v15, v0
	v_mov_b32_e32 v20, v0
	v_mov_b32_e32 v21, v0
	v_mov_b32_e32 v22, v0
	v_mov_b32_e32 v23, v0
	v_mov_b32_e32 v28, v0
	v_mov_b32_e32 v29, v0
	v_mov_b32_e32 v30, v0
	v_mov_b32_e32 v31, v0
	v_mov_b32_e32 v36, v0
	v_mov_b32_e32 v37, v0
	v_mov_b32_e32 v38, v0
	v_mov_b32_e32 v39, v0
	v_mov_b32_e32 v44, v0
	v_mov_b32_e32 v45, v0
	v_mov_b32_e32 v46, v0
	v_mov_b32_e32 v47, v0
	v_mov_b32_e32 v16, v0
	v_mov_b32_e32 v17, v0
	v_mov_b32_e32 v18, v0
	v_mov_b32_e32 v19, v0
	v_mov_b32_e32 v24, v0
	v_mov_b32_e32 v25, v0
	v_mov_b32_e32 v26, v0
	v_mov_b32_e32 v27, v0
	v_mov_b32_e32 v32, v0
	v_mov_b32_e32 v33, v0
	v_mov_b32_e32 v34, v0
	v_mov_b32_e32 v35, v0
	v_mov_b32_e32 v40, v0
	v_mov_b32_e32 v41, v0
	v_mov_b32_e32 v42, v0
	v_mov_b32_e32 v43, v0
	v_mov_b32_e32 v48, v0
	v_mov_b32_e32 v49, v0
	v_mov_b32_e32 v50, v0
	v_mov_b32_e32 v51, v0
	v_mov_b32_e32 v52, v0
	v_mov_b32_e32 v53, v0
	v_mov_b32_e32 v54, v0
	v_mov_b32_e32 v55, v0
	v_mov_b32_e32 v56, v0
	v_mov_b32_e32 v57, v0
	v_mov_b32_e32 v58, v0
	v_mov_b32_e32 v59, v0
	v_mov_b32_e32 v60, v0
	v_mov_b32_e32 v61, v0
	v_mov_b32_e32 v62, v0
	v_mov_b32_e32 v63, v0
	v_mov_b32_e32 v64, v0
	v_mov_b32_e32 v65, v0
	v_mov_b32_e32 v66, v0
	v_mov_b32_e32 v67, v0
	v_mov_b32_e32 v68, v0
	v_mov_b32_e32 v69, v0
	v_mov_b32_e32 v70, v0
	v_mov_b32_e32 v71, v0
	v_mov_b32_e32 v72, v0
	v_mov_b32_e32 v73, v0
	v_mov_b32_e32 v74, v0
	v_mov_b32_e32 v75, v0
	v_mov_b32_e32 v76, v0
	v_mov_b32_e32 v77, v0
	v_mov_b32_e32 v78, v0
	v_mov_b32_e32 v79, v0
	v_mov_b32_e32 v88, v0
	v_mov_b32_e32 v89, v0
	v_mov_b32_e32 v90, v0
	v_mov_b32_e32 v91, v0
	v_mov_b32_e32 v92, v0
	v_mov_b32_e32 v93, v0
	v_mov_b32_e32 v94, v0
	v_mov_b32_e32 v95, v0
	v_mov_b32_e32 v104, v0
	v_mov_b32_e32 v105, v0
	v_mov_b32_e32 v106, v0
	v_mov_b32_e32 v107, v0
	v_mov_b32_e32 v108, v0
	v_mov_b32_e32 v109, v0
	v_mov_b32_e32 v110, v0
	v_mov_b32_e32 v111, v0
	v_mov_b32_e32 v80, v0
	v_mov_b32_e32 v81, v0
	v_mov_b32_e32 v82, v0
	v_mov_b32_e32 v83, v0
	v_mov_b32_e32 v84, v0
	v_mov_b32_e32 v85, v0
	v_mov_b32_e32 v86, v0
	v_mov_b32_e32 v87, v0
	v_mov_b32_e32 v96, v0
	v_mov_b32_e32 v97, v0
	v_mov_b32_e32 v98, v0
	v_mov_b32_e32 v99, v0
	v_mov_b32_e32 v100, v0
	v_mov_b32_e32 v101, v0
	v_mov_b32_e32 v102, v0
	v_mov_b32_e32 v103, v0
	v_mov_b32_e32 v112, v0
	v_mov_b32_e32 v113, v0
	v_mov_b32_e32 v114, v0
	v_mov_b32_e32 v115, v0
	v_mov_b32_e32 v116, v0
	v_mov_b32_e32 v117, v0
	v_mov_b32_e32 v118, v0
	v_mov_b32_e32 v119, v0
	v_mov_b32_e32 v120, v0
	v_mov_b32_e32 v121, v0
	v_mov_b32_e32 v122, v0
	v_mov_b32_e32 v123, v0
	v_mov_b32_e32 v124, v0
	v_mov_b32_e32 v125, v0
	v_mov_b32_e32 v126, v0
	v_mov_b32_e32 v127, v0
	.p2alignl 6, 3212836864

.LBB0_849:
	s_ashr_i32 s67, s66, 31
	v_cmp_lt_i64_e32 vcc, s[0:1], v[136:137]
	s_lshl_b64 s[0:1], s[66:67], 20
	s_add_u32 s68, s8, s0
	s_addc_u32 s69, s9, s1
	s_and_b64 s[0:1], vcc, exec
	s_cselect_b32 s0, s69, s75
	s_cselect_b32 s1, s68, s74
	s_ashr_i32 s61, s60, 31
	s_lshl_b64 s[4:5], s[60:61], 20
	s_add_u32 s70, s64, s4
	s_addc_u32 s71, s65, s5
	s_and_b64 s[4:5], vcc, exec
	s_cselect_b32 s46, s71, s51
	s_cselect_b32 s47, s70, s50
	s_add_u32 s61, s50, 0x100
	v_mov_b32_e32 v0, 0
	s_addc_u32 s67, s51, 0
	s_mov_b32 s73, -2
	v_mov_b32_e32 v1, v0
	v_mov_b32_e32 v2, v0
	v_mov_b32_e32 v3, v0
	v_mov_b32_e32 v20, v0
	v_mov_b32_e32 v21, v0
	v_mov_b32_e32 v22, v0
	v_mov_b32_e32 v23, v0
	v_mov_b32_e32 v4, v0
	v_mov_b32_e32 v5, v0
	v_mov_b32_e32 v6, v0
	v_mov_b32_e32 v7, v0
	v_mov_b32_e32 v28, v0
	v_mov_b32_e32 v29, v0
	v_mov_b32_e32 v30, v0
	v_mov_b32_e32 v31, v0
	v_mov_b32_e32 v8, v0
	v_mov_b32_e32 v9, v0
	v_mov_b32_e32 v10, v0
	v_mov_b32_e32 v11, v0
	v_mov_b32_e32 v36, v0
	v_mov_b32_e32 v37, v0
	v_mov_b32_e32 v38, v0
	v_mov_b32_e32 v39, v0
	v_mov_b32_e32 v12, v0
	v_mov_b32_e32 v13, v0
	v_mov_b32_e32 v14, v0
	v_mov_b32_e32 v15, v0
	v_mov_b32_e32 v44, v0
	v_mov_b32_e32 v45, v0
	v_mov_b32_e32 v46, v0
	v_mov_b32_e32 v47, v0
	v_mov_b32_e32 v56, v0
	v_mov_b32_e32 v57, v0
	v_mov_b32_e32 v58, v0
	v_mov_b32_e32 v59, v0
	v_mov_b32_e32 v84, v0
	v_mov_b32_e32 v85, v0
	v_mov_b32_e32 v86, v0
	v_mov_b32_e32 v87, v0
	v_mov_b32_e32 v64, v0
	v_mov_b32_e32 v65, v0
	v_mov_b32_e32 v66, v0
	v_mov_b32_e32 v67, v0
	v_mov_b32_e32 v92, v0
	v_mov_b32_e32 v93, v0
	v_mov_b32_e32 v94, v0
	v_mov_b32_e32 v95, v0
	v_mov_b32_e32 v72, v0
	v_mov_b32_e32 v73, v0
	v_mov_b32_e32 v74, v0
	v_mov_b32_e32 v75, v0
	v_mov_b32_e32 v104, v0
	v_mov_b32_e32 v105, v0
	v_mov_b32_e32 v106, v0
	v_mov_b32_e32 v107, v0
	v_mov_b32_e32 v76, v0
	v_mov_b32_e32 v77, v0
	v_mov_b32_e32 v78, v0
	v_mov_b32_e32 v79, v0
	v_mov_b32_e32 v108, v0
	v_mov_b32_e32 v109, v0
	v_mov_b32_e32 v110, v0
	v_mov_b32_e32 v111, v0
	v_mov_b32_e32 v16, v0
	v_mov_b32_e32 v17, v0
	v_mov_b32_e32 v18, v0
	v_mov_b32_e32 v19, v0
	v_mov_b32_e32 v48, v0
	v_mov_b32_e32 v49, v0
	v_mov_b32_e32 v50, v0
	v_mov_b32_e32 v51, v0
	v_mov_b32_e32 v24, v0
	v_mov_b32_e32 v25, v0
	v_mov_b32_e32 v26, v0
	v_mov_b32_e32 v27, v0
	v_mov_b32_e32 v52, v0
	v_mov_b32_e32 v53, v0
	v_mov_b32_e32 v54, v0
	v_mov_b32_e32 v55, v0
	v_mov_b32_e32 v32, v0
	v_mov_b32_e32 v33, v0
	v_mov_b32_e32 v34, v0
	v_mov_b32_e32 v35, v0
	v_mov_b32_e32 v60, v0
	v_mov_b32_e32 v61, v0
	v_mov_b32_e32 v62, v0
	v_mov_b32_e32 v63, v0
	v_mov_b32_e32 v40, v0
	v_mov_b32_e32 v41, v0
	v_mov_b32_e32 v42, v0
	v_mov_b32_e32 v43, v0
	v_mov_b32_e32 v68, v0
	v_mov_b32_e32 v69, v0
	v_mov_b32_e32 v70, v0
	v_mov_b32_e32 v71, v0
	v_mov_b32_e32 v80, v0
	v_mov_b32_e32 v81, v0
	v_mov_b32_e32 v82, v0
	v_mov_b32_e32 v83, v0
	v_mov_b32_e32 v112, v0
	v_mov_b32_e32 v113, v0
	v_mov_b32_e32 v114, v0
	v_mov_b32_e32 v115, v0
	v_mov_b32_e32 v88, v0
	v_mov_b32_e32 v89, v0
	v_mov_b32_e32 v90, v0
	v_mov_b32_e32 v91, v0
	v_mov_b32_e32 v116, v0
	v_mov_b32_e32 v117, v0
	v_mov_b32_e32 v118, v0
	v_mov_b32_e32 v119, v0
	v_mov_b32_e32 v96, v0
	v_mov_b32_e32 v97, v0
	v_mov_b32_e32 v98, v0
	v_mov_b32_e32 v99, v0
	v_mov_b32_e32 v120, v0
	v_mov_b32_e32 v121, v0
	v_mov_b32_e32 v122, v0
	v_mov_b32_e32 v123, v0
	v_mov_b32_e32 v100, v0
	v_mov_b32_e32 v101, v0
	v_mov_b32_e32 v102, v0
	v_mov_b32_e32 v103, v0
	v_mov_b32_e32 v124, v0
	v_mov_b32_e32 v125, v0
	v_mov_b32_e32 v126, v0
	v_mov_b32_e32 v127, v0
	.p2alignl 6, 3212836864

.LBB0_985:
	s_ashr_i32 s13, s12, 31
	v_cmp_lt_i64_e32 vcc, s[0:1], v[142:143]
	s_lshl_b64 s[0:1], s[12:13], 20
	s_add_u32 s14, s38, s0
	s_addc_u32 s15, s39, s1
	s_and_b64 s[0:1], vcc, exec
	s_cselect_b32 s0, s15, s37
	s_cselect_b32 s1, s14, s36
	s_ashr_i32 s11, s10, 31
	s_lshl_b64 s[4:5], s[10:11], 20
	s_add_u32 s16, s62, s4
	s_addc_u32 s17, s63, s5
	s_and_b64 s[4:5], vcc, exec
	s_cselect_b32 s11, s17, s51
	s_cselect_b32 s13, s16, s50
	s_add_u32 s60, s36, 0x80080
	s_addc_u32 s61, s37, 0
	s_add_u32 s36, s50, 0x100
	v_mov_b32_e32 v0, 0
	s_addc_u32 s37, s51, 0
	s_mov_b32 s64, -2
	v_mov_b32_e32 v1, v0
	v_mov_b32_e32 v2, v0
	v_mov_b32_e32 v3, v0
	v_mov_b32_e32 v4, v0
	v_mov_b32_e32 v5, v0
	v_mov_b32_e32 v6, v0
	v_mov_b32_e32 v7, v0
	v_mov_b32_e32 v16, v0
	v_mov_b32_e32 v17, v0
	v_mov_b32_e32 v18, v0
	v_mov_b32_e32 v19, v0
	v_mov_b32_e32 v20, v0
	v_mov_b32_e32 v21, v0
	v_mov_b32_e32 v22, v0
	v_mov_b32_e32 v23, v0
	v_mov_b32_e32 v32, v0
	v_mov_b32_e32 v33, v0
	v_mov_b32_e32 v34, v0
	v_mov_b32_e32 v35, v0
	v_mov_b32_e32 v36, v0
	v_mov_b32_e32 v37, v0
	v_mov_b32_e32 v38, v0
	v_mov_b32_e32 v39, v0
	v_mov_b32_e32 v48, v0
	v_mov_b32_e32 v49, v0
	v_mov_b32_e32 v50, v0
	v_mov_b32_e32 v51, v0
	v_mov_b32_e32 v52, v0
	v_mov_b32_e32 v53, v0
	v_mov_b32_e32 v54, v0
	v_mov_b32_e32 v55, v0
	v_mov_b32_e32 v8, v0
	v_mov_b32_e32 v9, v0
	v_mov_b32_e32 v10, v0
	v_mov_b32_e32 v11, v0
	v_mov_b32_e32 v12, v0
	v_mov_b32_e32 v13, v0
	v_mov_b32_e32 v14, v0
	v_mov_b32_e32 v15, v0
	v_mov_b32_e32 v24, v0
	v_mov_b32_e32 v25, v0
	v_mov_b32_e32 v26, v0
	v_mov_b32_e32 v27, v0
	v_mov_b32_e32 v28, v0
	v_mov_b32_e32 v29, v0
	v_mov_b32_e32 v30, v0
	v_mov_b32_e32 v31, v0
	v_mov_b32_e32 v40, v0
	v_mov_b32_e32 v41, v0
	v_mov_b32_e32 v42, v0
	v_mov_b32_e32 v43, v0
	v_mov_b32_e32 v44, v0
	v_mov_b32_e32 v45, v0
	v_mov_b32_e32 v46, v0
	v_mov_b32_e32 v47, v0
	v_mov_b32_e32 v56, v0
	v_mov_b32_e32 v57, v0
	v_mov_b32_e32 v58, v0
	v_mov_b32_e32 v59, v0
	v_mov_b32_e32 v60, v0
	v_mov_b32_e32 v61, v0
	v_mov_b32_e32 v62, v0
	v_mov_b32_e32 v63, v0
	v_mov_b32_e32 v64, v0
	v_mov_b32_e32 v65, v0
	v_mov_b32_e32 v66, v0
	v_mov_b32_e32 v67, v0
	v_mov_b32_e32 v68, v0
	v_mov_b32_e32 v69, v0
	v_mov_b32_e32 v70, v0
	v_mov_b32_e32 v71, v0
	v_mov_b32_e32 v80, v0
	v_mov_b32_e32 v81, v0
	v_mov_b32_e32 v82, v0
	v_mov_b32_e32 v83, v0
	v_mov_b32_e32 v84, v0
	v_mov_b32_e32 v85, v0
	v_mov_b32_e32 v86, v0
	v_mov_b32_e32 v87, v0
	v_mov_b32_e32 v96, v0
	v_mov_b32_e32 v97, v0
	v_mov_b32_e32 v98, v0
	v_mov_b32_e32 v99, v0
	v_mov_b32_e32 v100, v0
	v_mov_b32_e32 v101, v0
	v_mov_b32_e32 v102, v0
	v_mov_b32_e32 v103, v0
	v_mov_b32_e32 v112, v0
	v_mov_b32_e32 v113, v0
	v_mov_b32_e32 v114, v0
	v_mov_b32_e32 v115, v0
	v_mov_b32_e32 v116, v0
	v_mov_b32_e32 v117, v0
	v_mov_b32_e32 v118, v0
	v_mov_b32_e32 v119, v0
	v_mov_b32_e32 v72, v0
	v_mov_b32_e32 v73, v0
	v_mov_b32_e32 v74, v0
	v_mov_b32_e32 v75, v0
	v_mov_b32_e32 v76, v0
	v_mov_b32_e32 v77, v0
	v_mov_b32_e32 v78, v0
	v_mov_b32_e32 v79, v0
	v_mov_b32_e32 v88, v0
	v_mov_b32_e32 v89, v0
	v_mov_b32_e32 v90, v0
	v_mov_b32_e32 v91, v0
	v_mov_b32_e32 v92, v0
	v_mov_b32_e32 v93, v0
	v_mov_b32_e32 v94, v0
	v_mov_b32_e32 v95, v0
	v_mov_b32_e32 v104, v0
	v_mov_b32_e32 v105, v0
	v_mov_b32_e32 v106, v0
	v_mov_b32_e32 v107, v0
	v_mov_b32_e32 v108, v0
	v_mov_b32_e32 v109, v0
	v_mov_b32_e32 v110, v0
	v_mov_b32_e32 v111, v0
	v_mov_b32_e32 v120, v0
	v_mov_b32_e32 v121, v0
	v_mov_b32_e32 v122, v0
	v_mov_b32_e32 v123, v0
	v_mov_b32_e32 v124, v0
	v_mov_b32_e32 v125, v0
	v_mov_b32_e32 v126, v0
	v_mov_b32_e32 v127, v0
	.p2alignl 6, 3212836864

.LBB0_1097:
	s_add_u32 s0, s64, 0x100
	v_mov_b32_e32 v0, 0
	s_addc_u32 s1, s65, 0
	s_mov_b32 s76, -2
	v_mov_b32_e32 v1, v0
	v_mov_b32_e32 v2, v0
	v_mov_b32_e32 v3, v0
	v_mov_b32_e32 v16, v0
	v_mov_b32_e32 v17, v0
	v_mov_b32_e32 v18, v0
	v_mov_b32_e32 v19, v0
	v_mov_b32_e32 v4, v0
	v_mov_b32_e32 v5, v0
	v_mov_b32_e32 v6, v0
	v_mov_b32_e32 v7, v0
	v_mov_b32_e32 v20, v0
	v_mov_b32_e32 v21, v0
	v_mov_b32_e32 v22, v0
	v_mov_b32_e32 v23, v0
	v_mov_b32_e32 v8, v0
	v_mov_b32_e32 v9, v0
	v_mov_b32_e32 v10, v0
	v_mov_b32_e32 v11, v0
	v_mov_b32_e32 v24, v0
	v_mov_b32_e32 v25, v0
	v_mov_b32_e32 v26, v0
	v_mov_b32_e32 v27, v0
	v_mov_b32_e32 v12, v0
	v_mov_b32_e32 v13, v0
	v_mov_b32_e32 v14, v0
	v_mov_b32_e32 v15, v0
	v_mov_b32_e32 v32, v0
	v_mov_b32_e32 v33, v0
	v_mov_b32_e32 v34, v0
	v_mov_b32_e32 v35, v0
	v_mov_b32_e32 v52, v0
	v_mov_b32_e32 v53, v0
	v_mov_b32_e32 v54, v0
	v_mov_b32_e32 v55, v0
	v_mov_b32_e32 v80, v0
	v_mov_b32_e32 v81, v0
	v_mov_b32_e32 v82, v0
	v_mov_b32_e32 v83, v0
	v_mov_b32_e32 v60, v0
	v_mov_b32_e32 v61, v0
	v_mov_b32_e32 v62, v0
	v_mov_b32_e32 v63, v0
	v_mov_b32_e32 v88, v0
	v_mov_b32_e32 v89, v0
	v_mov_b32_e32 v90, v0
	v_mov_b32_e32 v91, v0
	v_mov_b32_e32 v68, v0
	v_mov_b32_e32 v69, v0
	v_mov_b32_e32 v70, v0
	v_mov_b32_e32 v71, v0
	v_mov_b32_e32 v104, v0
	v_mov_b32_e32 v105, v0
	v_mov_b32_e32 v106, v0
	v_mov_b32_e32 v107, v0
	v_mov_b32_e32 v76, v0
	v_mov_b32_e32 v77, v0
	v_mov_b32_e32 v78, v0
	v_mov_b32_e32 v79, v0
	v_mov_b32_e32 v108, v0
	v_mov_b32_e32 v109, v0
	v_mov_b32_e32 v110, v0
	v_mov_b32_e32 v111, v0
	v_mov_b32_e32 v28, v0
	v_mov_b32_e32 v29, v0
	v_mov_b32_e32 v30, v0
	v_mov_b32_e32 v31, v0
	v_mov_b32_e32 v48, v0
	v_mov_b32_e32 v49, v0
	v_mov_b32_e32 v50, v0
	v_mov_b32_e32 v51, v0
	v_mov_b32_e32 v36, v0
	v_mov_b32_e32 v37, v0
	v_mov_b32_e32 v38, v0
	v_mov_b32_e32 v39, v0
	v_mov_b32_e32 v56, v0
	v_mov_b32_e32 v57, v0
	v_mov_b32_e32 v58, v0
	v_mov_b32_e32 v59, v0
	v_mov_b32_e32 v40, v0
	v_mov_b32_e32 v41, v0
	v_mov_b32_e32 v42, v0
	v_mov_b32_e32 v43, v0
	v_mov_b32_e32 v64, v0
	v_mov_b32_e32 v65, v0
	v_mov_b32_e32 v66, v0
	v_mov_b32_e32 v67, v0
	v_mov_b32_e32 v44, v0
	v_mov_b32_e32 v45, v0
	v_mov_b32_e32 v46, v0
	v_mov_b32_e32 v47, v0
	v_mov_b32_e32 v72, v0
	v_mov_b32_e32 v73, v0
	v_mov_b32_e32 v74, v0
	v_mov_b32_e32 v75, v0
	v_mov_b32_e32 v84, v0
	v_mov_b32_e32 v85, v0
	v_mov_b32_e32 v86, v0
	v_mov_b32_e32 v87, v0
	v_mov_b32_e32 v112, v0
	v_mov_b32_e32 v113, v0
	v_mov_b32_e32 v114, v0
	v_mov_b32_e32 v115, v0
	v_mov_b32_e32 v92, v0
	v_mov_b32_e32 v93, v0
	v_mov_b32_e32 v94, v0
	v_mov_b32_e32 v95, v0
	v_mov_b32_e32 v116, v0
	v_mov_b32_e32 v117, v0
	v_mov_b32_e32 v118, v0
	v_mov_b32_e32 v119, v0
	v_mov_b32_e32 v96, v0
	v_mov_b32_e32 v97, v0
	v_mov_b32_e32 v98, v0
	v_mov_b32_e32 v99, v0
	v_mov_b32_e32 v120, v0
	v_mov_b32_e32 v121, v0
	v_mov_b32_e32 v122, v0
	v_mov_b32_e32 v123, v0
	v_mov_b32_e32 v100, v0
	v_mov_b32_e32 v101, v0
	v_mov_b32_e32 v102, v0
	v_mov_b32_e32 v103, v0
	v_mov_b32_e32 v124, v0
	v_mov_b32_e32 v125, v0
	v_mov_b32_e32 v126, v0
	v_mov_b32_e32 v127, v0
	.p2alignl 6, 3212836864

.LBB0_1233:
	s_ashr_i32 s15, s14, 31
	v_cmp_lt_i64_e32 vcc, s[0:1], v[148:149]
	s_lshl_b64 s[0:1], s[14:15], 20
	s_add_u32 s16, s38, s0
	s_addc_u32 s17, s39, s1
	s_and_b64 s[0:1], vcc, exec
	s_cselect_b32 s0, s17, s37
	s_cselect_b32 s1, s16, s36
	s_ashr_i32 s13, s12, 31
	s_lshl_b64 s[4:5], s[12:13], 20
	s_add_u32 s18, s54, s4
	s_addc_u32 s19, s55, s5
	s_and_b64 s[4:5], vcc, exec
	s_cselect_b32 s13, s19, s59
	s_cselect_b32 s15, s18, s58
	s_add_u32 s46, s36, 0x80080
	s_addc_u32 s47, s37, 0
	s_add_u32 s36, s58, 0x100
	v_mov_b32_e32 v0, 0
	s_addc_u32 s37, s59, 0
	s_mov_b32 s64, -2
	v_mov_b32_e32 v1, v0
	v_mov_b32_e32 v2, v0
	v_mov_b32_e32 v3, v0
	v_mov_b32_e32 v4, v0
	v_mov_b32_e32 v5, v0
	v_mov_b32_e32 v6, v0
	v_mov_b32_e32 v7, v0
	v_mov_b32_e32 v8, v0
	v_mov_b32_e32 v9, v0
	v_mov_b32_e32 v10, v0
	v_mov_b32_e32 v11, v0
	v_mov_b32_e32 v12, v0
	v_mov_b32_e32 v13, v0
	v_mov_b32_e32 v14, v0
	v_mov_b32_e32 v15, v0
	v_mov_b32_e32 v16, v0
	v_mov_b32_e32 v17, v0
	v_mov_b32_e32 v18, v0
	v_mov_b32_e32 v19, v0
	v_mov_b32_e32 v20, v0
	v_mov_b32_e32 v21, v0
	v_mov_b32_e32 v22, v0
	v_mov_b32_e32 v23, v0
	v_mov_b32_e32 v24, v0
	v_mov_b32_e32 v25, v0
	v_mov_b32_e32 v26, v0
	v_mov_b32_e32 v27, v0
	v_mov_b32_e32 v28, v0
	v_mov_b32_e32 v29, v0
	v_mov_b32_e32 v30, v0
	v_mov_b32_e32 v31, v0
	v_mov_b32_e32 v56, v0
	v_mov_b32_e32 v57, v0
	v_mov_b32_e32 v58, v0
	v_mov_b32_e32 v59, v0
	v_mov_b32_e32 v60, v0
	v_mov_b32_e32 v61, v0
	v_mov_b32_e32 v62, v0
	v_mov_b32_e32 v63, v0
	v_mov_b32_e32 v72, v0
	v_mov_b32_e32 v73, v0
	v_mov_b32_e32 v74, v0
	v_mov_b32_e32 v75, v0
	v_mov_b32_e32 v76, v0
	v_mov_b32_e32 v77, v0
	v_mov_b32_e32 v78, v0
	v_mov_b32_e32 v79, v0
	v_mov_b32_e32 v80, v0
	v_mov_b32_e32 v81, v0
	v_mov_b32_e32 v82, v0
	v_mov_b32_e32 v83, v0
	v_mov_b32_e32 v84, v0
	v_mov_b32_e32 v85, v0
	v_mov_b32_e32 v86, v0
	v_mov_b32_e32 v87, v0
	v_mov_b32_e32 v88, v0
	v_mov_b32_e32 v89, v0
	v_mov_b32_e32 v90, v0
	v_mov_b32_e32 v91, v0
	v_mov_b32_e32 v92, v0
	v_mov_b32_e32 v93, v0
	v_mov_b32_e32 v94, v0
	v_mov_b32_e32 v95, v0
	v_mov_b32_e32 v32, v0
	v_mov_b32_e32 v33, v0
	v_mov_b32_e32 v34, v0
	v_mov_b32_e32 v35, v0
	v_mov_b32_e32 v36, v0
	v_mov_b32_e32 v37, v0
	v_mov_b32_e32 v38, v0
	v_mov_b32_e32 v39, v0
	v_mov_b32_e32 v40, v0
	v_mov_b32_e32 v41, v0
	v_mov_b32_e32 v42, v0
	v_mov_b32_e32 v43, v0
	v_mov_b32_e32 v44, v0
	v_mov_b32_e32 v45, v0
	v_mov_b32_e32 v46, v0
	v_mov_b32_e32 v47, v0
	v_mov_b32_e32 v48, v0
	v_mov_b32_e32 v49, v0
	v_mov_b32_e32 v50, v0
	v_mov_b32_e32 v51, v0
	v_mov_b32_e32 v52, v0
	v_mov_b32_e32 v53, v0
	v_mov_b32_e32 v54, v0
	v_mov_b32_e32 v55, v0
	v_mov_b32_e32 v64, v0
	v_mov_b32_e32 v65, v0
	v_mov_b32_e32 v66, v0
	v_mov_b32_e32 v67, v0
	v_mov_b32_e32 v68, v0
	v_mov_b32_e32 v69, v0
	v_mov_b32_e32 v70, v0
	v_mov_b32_e32 v71, v0
	v_mov_b32_e32 v96, v0
	v_mov_b32_e32 v97, v0
	v_mov_b32_e32 v98, v0
	v_mov_b32_e32 v99, v0
	v_mov_b32_e32 v100, v0
	v_mov_b32_e32 v101, v0
	v_mov_b32_e32 v102, v0
	v_mov_b32_e32 v103, v0
	v_mov_b32_e32 v104, v0
	v_mov_b32_e32 v105, v0
	v_mov_b32_e32 v106, v0
	v_mov_b32_e32 v107, v0
	v_mov_b32_e32 v108, v0
	v_mov_b32_e32 v109, v0
	v_mov_b32_e32 v110, v0
	v_mov_b32_e32 v111, v0
	v_mov_b32_e32 v112, v0
	v_mov_b32_e32 v113, v0
	v_mov_b32_e32 v114, v0
	v_mov_b32_e32 v115, v0
	v_mov_b32_e32 v116, v0
	v_mov_b32_e32 v117, v0
	v_mov_b32_e32 v118, v0
	v_mov_b32_e32 v119, v0
	v_mov_b32_e32 v120, v0
	v_mov_b32_e32 v121, v0
	v_mov_b32_e32 v122, v0
	v_mov_b32_e32 v123, v0
	v_mov_b32_e32 v124, v0
	v_mov_b32_e32 v125, v0
	v_mov_b32_e32 v126, v0
	v_mov_b32_e32 v127, v0
	.p2alignl 6, 3212836864

.LBB0_1532:
	s_ashr_i32 s61, s60, 31
	v_cmp_lt_i64_e32 vcc, s[0:1], v[146:147]
	s_lshl_b64 s[0:1], s[60:61], 20
	s_add_u32 s62, s38, s0
	s_addc_u32 s63, s39, s1
	s_and_b64 s[0:1], vcc, exec
	s_cselect_b32 s0, s63, s9
	s_cselect_b32 s1, s62, s8
	s_ashr_i32 s59, s58, 31
	s_lshl_b64 s[4:5], s[58:59], 20
	v_readlane_b32 s42, v255, 26
	v_readlane_b32 s43, v255, 27
	s_add_u32 s64, s42, s4
	s_addc_u32 s65, s43, s5
	s_and_b64 s[4:5], vcc, exec
	s_cselect_b32 s59, s65, s69
	s_cselect_b32 s61, s64, s68
	s_add_u32 s76, s68, 0x100
	v_mov_b32_e32 v0, 0
	s_addc_u32 s77, s69, 0
	s_mov_b32 s78, -2
	v_mov_b32_e32 v1, v0
	v_mov_b32_e32 v2, v0
	v_mov_b32_e32 v3, v0
	v_mov_b32_e32 v32, v0
	v_mov_b32_e32 v33, v0
	v_mov_b32_e32 v34, v0
	v_mov_b32_e32 v35, v0
	v_mov_b32_e32 v4, v0
	v_mov_b32_e32 v5, v0
	v_mov_b32_e32 v6, v0
	v_mov_b32_e32 v7, v0
	v_mov_b32_e32 v36, v0
	v_mov_b32_e32 v37, v0
	v_mov_b32_e32 v38, v0
	v_mov_b32_e32 v39, v0
	v_mov_b32_e32 v8, v0
	v_mov_b32_e32 v9, v0
	v_mov_b32_e32 v10, v0
	v_mov_b32_e32 v11, v0
	v_mov_b32_e32 v40, v0
	v_mov_b32_e32 v41, v0
	v_mov_b32_e32 v42, v0
	v_mov_b32_e32 v43, v0
	v_mov_b32_e32 v12, v0
	v_mov_b32_e32 v13, v0
	v_mov_b32_e32 v14, v0
	v_mov_b32_e32 v15, v0
	v_mov_b32_e32 v44, v0
	v_mov_b32_e32 v45, v0
	v_mov_b32_e32 v46, v0
	v_mov_b32_e32 v47, v0
	v_mov_b32_e32 v64, v0
	v_mov_b32_e32 v65, v0
	v_mov_b32_e32 v66, v0
	v_mov_b32_e32 v67, v0
	v_mov_b32_e32 v96, v0
	v_mov_b32_e32 v97, v0
	v_mov_b32_e32 v98, v0
	v_mov_b32_e32 v99, v0
	v_mov_b32_e32 v68, v0
	v_mov_b32_e32 v69, v0
	v_mov_b32_e32 v70, v0
	v_mov_b32_e32 v71, v0
	v_mov_b32_e32 v100, v0
	v_mov_b32_e32 v101, v0
	v_mov_b32_e32 v102, v0
	v_mov_b32_e32 v103, v0
	v_mov_b32_e32 v72, v0
	v_mov_b32_e32 v73, v0
	v_mov_b32_e32 v74, v0
	v_mov_b32_e32 v75, v0
	v_mov_b32_e32 v104, v0
	v_mov_b32_e32 v105, v0
	v_mov_b32_e32 v106, v0
	v_mov_b32_e32 v107, v0
	v_mov_b32_e32 v76, v0
	v_mov_b32_e32 v77, v0
	v_mov_b32_e32 v78, v0
	v_mov_b32_e32 v79, v0
	v_mov_b32_e32 v108, v0
	v_mov_b32_e32 v109, v0
	v_mov_b32_e32 v110, v0
	v_mov_b32_e32 v111, v0
	v_mov_b32_e32 v16, v0
	v_mov_b32_e32 v17, v0
	v_mov_b32_e32 v18, v0
	v_mov_b32_e32 v19, v0
	v_mov_b32_e32 v48, v0
	v_mov_b32_e32 v49, v0
	v_mov_b32_e32 v50, v0
	v_mov_b32_e32 v51, v0
	v_mov_b32_e32 v20, v0
	v_mov_b32_e32 v21, v0
	v_mov_b32_e32 v22, v0
	v_mov_b32_e32 v23, v0
	v_mov_b32_e32 v52, v0
	v_mov_b32_e32 v53, v0
	v_mov_b32_e32 v54, v0
	v_mov_b32_e32 v55, v0
	v_mov_b32_e32 v24, v0
	v_mov_b32_e32 v25, v0
	v_mov_b32_e32 v26, v0
	v_mov_b32_e32 v27, v0
	v_mov_b32_e32 v56, v0
	v_mov_b32_e32 v57, v0
	v_mov_b32_e32 v58, v0
	v_mov_b32_e32 v59, v0
	v_mov_b32_e32 v28, v0
	v_mov_b32_e32 v29, v0
	v_mov_b32_e32 v30, v0
	v_mov_b32_e32 v31, v0
	v_mov_b32_e32 v60, v0
	v_mov_b32_e32 v61, v0
	v_mov_b32_e32 v62, v0
	v_mov_b32_e32 v63, v0
	v_mov_b32_e32 v80, v0
	v_mov_b32_e32 v81, v0
	v_mov_b32_e32 v82, v0
	v_mov_b32_e32 v83, v0
	v_mov_b32_e32 v112, v0
	v_mov_b32_e32 v113, v0
	v_mov_b32_e32 v114, v0
	v_mov_b32_e32 v115, v0
	v_mov_b32_e32 v84, v0
	v_mov_b32_e32 v85, v0
	v_mov_b32_e32 v86, v0
	v_mov_b32_e32 v87, v0
	v_mov_b32_e32 v116, v0
	v_mov_b32_e32 v117, v0
	v_mov_b32_e32 v118, v0
	v_mov_b32_e32 v119, v0
	v_mov_b32_e32 v88, v0
	v_mov_b32_e32 v89, v0
	v_mov_b32_e32 v90, v0
	v_mov_b32_e32 v91, v0
	v_mov_b32_e32 v120, v0
	v_mov_b32_e32 v121, v0
	v_mov_b32_e32 v122, v0
	v_mov_b32_e32 v123, v0
	v_mov_b32_e32 v92, v0
	v_mov_b32_e32 v93, v0
	v_mov_b32_e32 v94, v0
	v_mov_b32_e32 v95, v0
	v_mov_b32_e32 v124, v0
	v_mov_b32_e32 v125, v0
	v_mov_b32_e32 v126, v0
	v_mov_b32_e32 v127, v0
	.p2alignl 6, 3212836864

.LBB0_1675:
	s_ashr_i32 s13, s12, 31
	v_cmp_lt_i64_e32 vcc, s[0:1], v[140:141]
	s_lshl_b64 s[0:1], s[12:13], 20
	s_add_u32 s14, s38, s0
	s_addc_u32 s15, s39, s1
	s_and_b64 s[0:1], vcc, exec
	s_cselect_b32 s0, s15, s21
	s_cselect_b32 s1, s14, s20
	s_ashr_i32 s11, s10, 31
	s_lshl_b64 s[4:5], s[10:11], 20
	s_add_u32 s16, s56, s4
	s_addc_u32 s17, s57, s5
	s_and_b64 s[4:5], vcc, exec
	s_cselect_b32 s11, s17, s45
	s_cselect_b32 s13, s16, s44
	s_add_u32 s20, s20, 0x80080
	s_addc_u32 s21, s21, 0
	s_add_u32 s51, s44, 0x100
	v_mov_b32_e32 v0, 0
	s_addc_u32 s52, s45, 0
	s_mov_b32 s53, -2
	v_mov_b32_e32 v1, v0
	v_mov_b32_e32 v2, v0
	v_mov_b32_e32 v3, v0
	v_mov_b32_e32 v4, v0
	v_mov_b32_e32 v5, v0
	v_mov_b32_e32 v6, v0
	v_mov_b32_e32 v7, v0
	v_mov_b32_e32 v16, v0
	v_mov_b32_e32 v17, v0
	v_mov_b32_e32 v18, v0
	v_mov_b32_e32 v19, v0
	v_mov_b32_e32 v20, v0
	v_mov_b32_e32 v21, v0
	v_mov_b32_e32 v22, v0
	v_mov_b32_e32 v23, v0
	v_mov_b32_e32 v32, v0
	v_mov_b32_e32 v33, v0
	v_mov_b32_e32 v34, v0
	v_mov_b32_e32 v35, v0
	v_mov_b32_e32 v36, v0
	v_mov_b32_e32 v37, v0
	v_mov_b32_e32 v38, v0
	v_mov_b32_e32 v39, v0
	v_mov_b32_e32 v48, v0
	v_mov_b32_e32 v49, v0
	v_mov_b32_e32 v50, v0
	v_mov_b32_e32 v51, v0
	v_mov_b32_e32 v52, v0
	v_mov_b32_e32 v53, v0
	v_mov_b32_e32 v54, v0
	v_mov_b32_e32 v55, v0
	v_mov_b32_e32 v8, v0
	v_mov_b32_e32 v9, v0
	v_mov_b32_e32 v10, v0
	v_mov_b32_e32 v11, v0
	v_mov_b32_e32 v12, v0
	v_mov_b32_e32 v13, v0
	v_mov_b32_e32 v14, v0
	v_mov_b32_e32 v15, v0
	v_mov_b32_e32 v24, v0
	v_mov_b32_e32 v25, v0
	v_mov_b32_e32 v26, v0
	v_mov_b32_e32 v27, v0
	v_mov_b32_e32 v28, v0
	v_mov_b32_e32 v29, v0
	v_mov_b32_e32 v30, v0
	v_mov_b32_e32 v31, v0
	v_mov_b32_e32 v40, v0
	v_mov_b32_e32 v41, v0
	v_mov_b32_e32 v42, v0
	v_mov_b32_e32 v43, v0
	v_mov_b32_e32 v44, v0
	v_mov_b32_e32 v45, v0
	v_mov_b32_e32 v46, v0
	v_mov_b32_e32 v47, v0
	v_mov_b32_e32 v56, v0
	v_mov_b32_e32 v57, v0
	v_mov_b32_e32 v58, v0
	v_mov_b32_e32 v59, v0
	v_mov_b32_e32 v60, v0
	v_mov_b32_e32 v61, v0
	v_mov_b32_e32 v62, v0
	v_mov_b32_e32 v63, v0
	v_mov_b32_e32 v64, v0
	v_mov_b32_e32 v65, v0
	v_mov_b32_e32 v66, v0
	v_mov_b32_e32 v67, v0
	v_mov_b32_e32 v68, v0
	v_mov_b32_e32 v69, v0
	v_mov_b32_e32 v70, v0
	v_mov_b32_e32 v71, v0
	v_mov_b32_e32 v80, v0
	v_mov_b32_e32 v81, v0
	v_mov_b32_e32 v82, v0
	v_mov_b32_e32 v83, v0
	v_mov_b32_e32 v84, v0
	v_mov_b32_e32 v85, v0
	v_mov_b32_e32 v86, v0
	v_mov_b32_e32 v87, v0
	v_mov_b32_e32 v96, v0
	v_mov_b32_e32 v97, v0
	v_mov_b32_e32 v98, v0
	v_mov_b32_e32 v99, v0
	v_mov_b32_e32 v100, v0
	v_mov_b32_e32 v101, v0
	v_mov_b32_e32 v102, v0
	v_mov_b32_e32 v103, v0
	v_mov_b32_e32 v112, v0
	v_mov_b32_e32 v113, v0
	v_mov_b32_e32 v114, v0
	v_mov_b32_e32 v115, v0
	v_mov_b32_e32 v116, v0
	v_mov_b32_e32 v117, v0
	v_mov_b32_e32 v118, v0
	v_mov_b32_e32 v119, v0
	v_mov_b32_e32 v72, v0
	v_mov_b32_e32 v73, v0
	v_mov_b32_e32 v74, v0
	v_mov_b32_e32 v75, v0
	v_mov_b32_e32 v76, v0
	v_mov_b32_e32 v77, v0
	v_mov_b32_e32 v78, v0
	v_mov_b32_e32 v79, v0
	v_mov_b32_e32 v88, v0
	v_mov_b32_e32 v89, v0
	v_mov_b32_e32 v90, v0
	v_mov_b32_e32 v91, v0
	v_mov_b32_e32 v92, v0
	v_mov_b32_e32 v93, v0
	v_mov_b32_e32 v94, v0
	v_mov_b32_e32 v95, v0
	v_mov_b32_e32 v104, v0
	v_mov_b32_e32 v105, v0
	v_mov_b32_e32 v106, v0
	v_mov_b32_e32 v107, v0
	v_mov_b32_e32 v108, v0
	v_mov_b32_e32 v109, v0
	v_mov_b32_e32 v110, v0
	v_mov_b32_e32 v111, v0
	v_mov_b32_e32 v120, v0
	v_mov_b32_e32 v121, v0
	v_mov_b32_e32 v122, v0
	v_mov_b32_e32 v123, v0
	v_mov_b32_e32 v124, v0
	v_mov_b32_e32 v125, v0
	v_mov_b32_e32 v126, v0
	v_mov_b32_e32 v127, v0
	.p2alignl 6, 3212836864

.LBB0_1748:
	s_add_u32 s0, s44, 0x100
	v_mov_b32_e32 v0, 0
	s_addc_u32 s1, s45, 0
	s_mov_b32 s61, -2
	v_mov_b32_e32 v1, v0
	v_mov_b32_e32 v2, v0
	v_mov_b32_e32 v3, v0
	v_mov_b32_e32 v16, v0
	v_mov_b32_e32 v17, v0
	v_mov_b32_e32 v18, v0
	v_mov_b32_e32 v19, v0
	v_mov_b32_e32 v4, v0
	v_mov_b32_e32 v5, v0
	v_mov_b32_e32 v6, v0
	v_mov_b32_e32 v7, v0
	v_mov_b32_e32 v20, v0
	v_mov_b32_e32 v21, v0
	v_mov_b32_e32 v22, v0
	v_mov_b32_e32 v23, v0
	v_mov_b32_e32 v8, v0
	v_mov_b32_e32 v9, v0
	v_mov_b32_e32 v10, v0
	v_mov_b32_e32 v11, v0
	v_mov_b32_e32 v24, v0
	v_mov_b32_e32 v25, v0
	v_mov_b32_e32 v26, v0
	v_mov_b32_e32 v27, v0
	v_mov_b32_e32 v12, v0
	v_mov_b32_e32 v13, v0
	v_mov_b32_e32 v14, v0
	v_mov_b32_e32 v15, v0
	v_mov_b32_e32 v32, v0
	v_mov_b32_e32 v33, v0
	v_mov_b32_e32 v34, v0
	v_mov_b32_e32 v35, v0
	v_mov_b32_e32 v52, v0
	v_mov_b32_e32 v53, v0
	v_mov_b32_e32 v54, v0
	v_mov_b32_e32 v55, v0
	v_mov_b32_e32 v80, v0
	v_mov_b32_e32 v81, v0
	v_mov_b32_e32 v82, v0
	v_mov_b32_e32 v83, v0
	v_mov_b32_e32 v60, v0
	v_mov_b32_e32 v61, v0
	v_mov_b32_e32 v62, v0
	v_mov_b32_e32 v63, v0
	v_mov_b32_e32 v88, v0
	v_mov_b32_e32 v89, v0
	v_mov_b32_e32 v90, v0
	v_mov_b32_e32 v91, v0
	v_mov_b32_e32 v68, v0
	v_mov_b32_e32 v69, v0
	v_mov_b32_e32 v70, v0
	v_mov_b32_e32 v71, v0
	v_mov_b32_e32 v104, v0
	v_mov_b32_e32 v105, v0
	v_mov_b32_e32 v106, v0
	v_mov_b32_e32 v107, v0
	v_mov_b32_e32 v76, v0
	v_mov_b32_e32 v77, v0
	v_mov_b32_e32 v78, v0
	v_mov_b32_e32 v79, v0
	v_mov_b32_e32 v108, v0
	v_mov_b32_e32 v109, v0
	v_mov_b32_e32 v110, v0
	v_mov_b32_e32 v111, v0
	v_mov_b32_e32 v28, v0
	v_mov_b32_e32 v29, v0
	v_mov_b32_e32 v30, v0
	v_mov_b32_e32 v31, v0
	v_mov_b32_e32 v48, v0
	v_mov_b32_e32 v49, v0
	v_mov_b32_e32 v50, v0
	v_mov_b32_e32 v51, v0
	v_mov_b32_e32 v36, v0
	v_mov_b32_e32 v37, v0
	v_mov_b32_e32 v38, v0
	v_mov_b32_e32 v39, v0
	v_mov_b32_e32 v56, v0
	v_mov_b32_e32 v57, v0
	v_mov_b32_e32 v58, v0
	v_mov_b32_e32 v59, v0
	v_mov_b32_e32 v40, v0
	v_mov_b32_e32 v41, v0
	v_mov_b32_e32 v42, v0
	v_mov_b32_e32 v43, v0
	v_mov_b32_e32 v64, v0
	v_mov_b32_e32 v65, v0
	v_mov_b32_e32 v66, v0
	v_mov_b32_e32 v67, v0
	v_mov_b32_e32 v44, v0
	v_mov_b32_e32 v45, v0
	v_mov_b32_e32 v46, v0
	v_mov_b32_e32 v47, v0
	v_mov_b32_e32 v72, v0
	v_mov_b32_e32 v73, v0
	v_mov_b32_e32 v74, v0
	v_mov_b32_e32 v75, v0
	v_mov_b32_e32 v84, v0
	v_mov_b32_e32 v85, v0
	v_mov_b32_e32 v86, v0
	v_mov_b32_e32 v87, v0
	v_mov_b32_e32 v112, v0
	v_mov_b32_e32 v113, v0
	v_mov_b32_e32 v114, v0
	v_mov_b32_e32 v115, v0
	v_mov_b32_e32 v92, v0
	v_mov_b32_e32 v93, v0
	v_mov_b32_e32 v94, v0
	v_mov_b32_e32 v95, v0
	v_mov_b32_e32 v116, v0
	v_mov_b32_e32 v117, v0
	v_mov_b32_e32 v118, v0
	v_mov_b32_e32 v119, v0
	v_mov_b32_e32 v96, v0
	v_mov_b32_e32 v97, v0
	v_mov_b32_e32 v98, v0
	v_mov_b32_e32 v99, v0
	v_mov_b32_e32 v120, v0
	v_mov_b32_e32 v121, v0
	v_mov_b32_e32 v122, v0
	v_mov_b32_e32 v123, v0
	v_mov_b32_e32 v100, v0
	v_mov_b32_e32 v101, v0
	v_mov_b32_e32 v102, v0
	v_mov_b32_e32 v103, v0
	v_mov_b32_e32 v124, v0
	v_mov_b32_e32 v125, v0
	v_mov_b32_e32 v126, v0
	v_mov_b32_e32 v127, v0
	.p2alignl 6, 3212836864
